# conv items: row loads prefetched three iterations deep, on top of the P1 LDS-DMA prefetch version
# speedup vs baseline: 1.0063x; 1.0063x over previous
; __device__ __forceinline__ unsigned pk2(float lo, float hi) { return pg8::cvt_pk_bf16(lo, hi); }
;     __device__ __forceinline__ void operator()(int item) const {
;     ...
;         const bool first = (m0 % T) == 0;
;         { v4u a = {0u, 0u, 0u, 0u}, bq = {0u, 0u, 0u, 0u};
;           if (!first) { a = *(const v4u*)(CUB + (size_t)(m0 - 2) * CW + ch); bq = *(const v4u*)(CUB + (size_t)(m0 - 1) * CW + ch); }
; #pragma unroll
;           for (int e = 0; e < 4; ++e) { p2[2 * e] = pg8::bflo(a[e]); p2[2 * e + 1] = pg8::bfhi(a[e]); p1[2 * e] = pg8::bflo(bq[e]); p1[2 * e + 1] = pg8::bfhi(bq[e]); } }
; #pragma unroll 4
;         for (int r = 0; r < 16; ++r) { const int m = m0 + r;
;             const v4u cv = *(const v4u*)(CUB + (size_t)m * CW + ch), gv = *(const v4u*)(GZB + (size_t)m * CW + ch);
;             float cur[8], o[8];
; #pragma unroll
;             for (int e = 0; e < 4; ++e) { cur[2 * e] = pg8::bflo(cv[e]); cur[2 * e + 1] = pg8::bfhi(cv[e]); }
; #pragma unroll
;             for (int e = 0; e < 4; ++e) { o[2 * e] = pg8::bflo(gv[e]) * (w0[2 * e] * p2[2 * e] + w1[2 * e] * p1[2 * e] + w2[2 * e] * cur[2 * e]);
;                 o[2 * e + 1] = pg8::bfhi(gv[e]) * (w0[2 * e + 1] * p2[2 * e + 1] + w1[2 * e + 1] * p1[2 * e + 1] + w2[2 * e + 1] * cur[2 * e + 1]); }
;             v4u ov; ov.x = pk2(o[0], o[1]); ov.y = pk2(o[2], o[3]); ov.z = pk2(o[4], o[5]); ov.w = pk2(o[6], o[7]);
;             *(v4u*)(OAB + (size_t)m * 1024 + 512 + ch) = ov;
.LBB0_420:
	s_lshl_b64 s[8:9], s[12:13], 11
	s_add_u32 s8, s6, s8
	s_addc_u32 s9, s7, s9
	s_lshl_b64 s[10:11], s[12:13], 10
	s_waitcnt vmcnt(2)
	v_mov_b32_e32 v1, v15
	v_mov_b32_e32 v15, v17
	v_mov_b32_e32 v17, v11
	v_mov_b32_e32 v11, v13
	s_add_u32 s10, s6, s10
	s_mov_b32 s43, 16
	s_waitcnt vmcnt(1)
	v_lshlrev_b32_e32 v35, 16, v30
	v_and_b32_e32 v37, 0xffff0000, v30
	s_waitcnt vmcnt(0)
	v_lshlrev_b32_e32 v44, 16, v26
	v_and_b32_e32 v46, 0xffff0000, v26
	v_lshlrev_b32_e32 v39, 16, v31
	v_and_b32_e32 v31, 0xffff0000, v31
	v_lshlrev_b32_e32 v48, 16, v27
	v_and_b32_e32 v50, 0xffff0000, v27
	v_lshlrev_b32_e32 v27, 16, v32
	v_and_b32_e32 v41, 0xffff0000, v32
	v_lshlrev_b32_e32 v52, 16, v28
	v_and_b32_e32 v28, 0xffff0000, v28
	v_lshlrev_b32_e32 v43, 16, v33
	v_and_b32_e32 v33, 0xffff0000, v33
	v_lshlrev_b32_e32 v54, 16, v29
	v_and_b32_e32 v56, 0xffff0000, v29
	v_mov_b32_e32 v13, v24
	v_mov_b32_e32 v24, v11
	v_mov_b32_e32 v11, v22
	v_mov_b32_e32 v22, v17
	v_mov_b32_e32 v17, v20
	v_mov_b32_e32 v20, v15
	v_mov_b32_e32 v15, v18
	v_mov_b32_e32 v18, v1
	s_addc_u32 s11, s7, s11
	v_lshl_add_u64 v[242:243], s[10:11], 0, v[210:211]
	s_mov_b32 s84, 0x0
	s_mov_b32 s85, 0
	v_lshl_add_u64 v[230:231], v[242:243], 0, s[84:85]
	v_add_co_u32_e32 v226, vcc, s59, v230
	s_nop 1
	v_addc_co_u32_e32 v227, vcc, 0, v231, vcc
	v_add_co_u32_e32 v228, vcc, s60, v230
	s_nop 1
	v_addc_co_u32_e32 v229, vcc, 0, v231, vcc
	global_load_dwordx4 v[100:103], v[226:227], off offset:0
	global_load_dwordx4 v[104:107], v[228:229], off offset:0
	global_load_dwordx4 v[108:111], v[226:227], off offset:1024
	global_load_dwordx4 v[112:115], v[228:229], off offset:1024
	global_load_dwordx4 v[116:119], v[226:227], off offset:2048
	global_load_dwordx4 v[120:123], v[228:229], off offset:2048
	global_load_dwordx4 v[124:127], v[226:227], off offset:3072
	global_load_dwordx4 v[128:131], v[228:229], off offset:3072
	s_mov_b32 s84, 0x1000
	s_mov_b32 s85, 0
	v_lshl_add_u64 v[230:231], v[242:243], 0, s[84:85]
	v_add_co_u32_e32 v226, vcc, s59, v230
	s_nop 1
	v_addc_co_u32_e32 v227, vcc, 0, v231, vcc
	v_add_co_u32_e32 v228, vcc, s60, v230
	s_nop 1
	v_addc_co_u32_e32 v229, vcc, 0, v231, vcc
	global_load_dwordx4 v[132:135], v[226:227], off offset:0
	global_load_dwordx4 v[136:139], v[228:229], off offset:0
	global_load_dwordx4 v[140:143], v[226:227], off offset:1024
	global_load_dwordx4 v[144:147], v[228:229], off offset:1024
	global_load_dwordx4 v[148:151], v[226:227], off offset:2048
	global_load_dwordx4 v[152:155], v[228:229], off offset:2048
	global_load_dwordx4 v[156:159], v[226:227], off offset:3072
	global_load_dwordx4 v[160:163], v[228:229], off offset:3072
	s_mov_b32 s84, 0x2000
	s_mov_b32 s85, 0
	v_lshl_add_u64 v[230:231], v[242:243], 0, s[84:85]
	v_add_co_u32_e32 v226, vcc, s59, v230
	s_nop 1
	v_addc_co_u32_e32 v227, vcc, 0, v231, vcc
	v_add_co_u32_e32 v228, vcc, s60, v230
	s_nop 1
	v_addc_co_u32_e32 v229, vcc, 0, v231, vcc
	global_load_dwordx4 v[164:167], v[226:227], off offset:0
	global_load_dwordx4 v[168:171], v[228:229], off offset:0
	global_load_dwordx4 v[172:175], v[226:227], off offset:1024
	global_load_dwordx4 v[176:179], v[228:229], off offset:1024
	global_load_dwordx4 v[180:183], v[226:227], off offset:2048
	global_load_dwordx4 v[184:187], v[228:229], off offset:2048
	global_load_dwordx4 v[188:191], v[226:227], off offset:3072
	global_load_dwordx4 v[192:195], v[228:229], off offset:3072
.LBB0_421:
	s_waitcnt vmcnt(16)
	s_nop 0
	v_lshl_add_u64 v[60:61], s[10:11], 0, v[210:211]
	v_add_co_u32_e32 v58, vcc, s59, v60
	v_lshl_add_u64 v[62:63], s[8:9], 0, v[210:211]
	s_nop 0
	v_addc_co_u32_e32 v59, vcc, 0, v61, vcc
	v_add_co_u32_e32 v60, vcc, s60, v60
	s_add_u32 s8, s8, 0x2000
	s_nop 0
	v_addc_co_u32_e32 v61, vcc, 0, v61, vcc
	v_add_co_u32_e32 v80, vcc, s61, v62
	s_addc_u32 s9, s9, 0
	s_nop 0
	v_addc_co_u32_e32 v81, vcc, 0, v63, vcc
	v_add_co_u32_e32 v62, vcc, s62, v62
	s_add_u32 s10, s10, 0x1000
	s_nop 0
	v_addc_co_u32_e32 v63, vcc, 0, v63, vcc
	s_addc_u32 s11, s11, 0
	s_add_i32 s43, s43, -4
	s_cmp_lg_u32 s43, 0
	v_and_b32_e32 v51, 0xffff0000, v101
	v_and_b32_e32 v29, 0xffff0000, v102
	v_and_b32_e32 v57, 0xffff0000, v103
	v_lshlrev_b32_e32 v45, 16, v100
	v_and_b32_e32 v47, 0xffff0000, v100
	v_lshlrev_b32_e32 v49, 16, v101
	v_lshlrev_b32_e32 v53, 16, v102
	v_lshlrev_b32_e32 v55, 16, v103
	v_pk_mul_f32 v[88:89], v[20:21], v[50:51]
	v_pk_mul_f32 v[92:93], v[22:23], v[28:29]
	v_pk_mul_f32 v[96:97], v[24:25], v[56:57]
	v_pk_mul_f32 v[82:83], v[14:15], v[44:45]
	v_pk_mul_f32 v[84:85], v[18:19], v[46:47]
	v_pk_mul_f32 v[86:87], v[16:17], v[48:49]
	v_pk_mul_f32 v[90:91], v[10:11], v[52:53]
	v_pk_mul_f32 v[94:95], v[12:13], v[54:55]
	v_fma_f32 v31, v9, v31, v88
	v_fma_f32 v41, v3, v41, v92
	v_fma_f32 v33, v5, v33, v96
	v_and_b32_e32 v32, 0xffff0000, v105
	v_and_b32_e32 v36, 0xffff0000, v106
	v_and_b32_e32 v40, 0xffff0000, v107
	v_fma_f32 v35, v6, v35, v82
	v_fma_f32 v37, v7, v37, v84
	v_fma_f32 v39, v8, v39, v86
	v_fma_f32 v27, v2, v27, v90
	v_fma_f32 v42, v4, v43, v94
	v_add_f32_e32 v31, v31, v89
	v_add_f32_e32 v41, v41, v93
	v_add_f32_e32 v33, v33, v97
	v_lshlrev_b32_e32 v1, 16, v104
	v_and_b32_e32 v26, 0xffff0000, v104
	v_lshlrev_b32_e32 v30, 16, v105
	v_lshlrev_b32_e32 v34, 16, v106
	v_lshlrev_b32_e32 v38, 16, v107
	v_add_f32_e32 v35, v35, v83
	v_add_f32_e32 v37, v37, v85
	v_add_f32_e32 v39, v39, v87
	v_add_f32_e32 v27, v27, v91
	v_add_f32_e32 v42, v42, v95
	v_mul_f32_e32 v31, v31, v32
	v_mul_f32_e32 v32, v41, v36
	v_mul_f32_e32 v33, v33, v40
	v_mul_f32_e32 v1, v35, v1
	v_mul_f32_e32 v26, v37, v26
	v_mul_f32_e32 v35, v39, v30
	v_mul_f32_e32 v27, v27, v34
	v_mul_f32_e32 v34, v42, v38
; __device__ __forceinline__ unsigned pk2(float lo, float hi) { return pg8::cvt_pk_bf16(lo, hi); }
;     __device__ __forceinline__ void operator()(int item) const {
;     ...
;         for (int r = 0; r < 16; ++r) { const int m = m0 + r;
;             const v4u cv = *(const v4u*)(CUB + (size_t)m * CW + ch), gv = *(const v4u*)(GZB + (size_t)m * CW + ch);
;             float cur[8], o[8];
; #pragma unroll
;             for (int e = 0; e < 4; ++e) { cur[2 * e] = pg8::bflo(cv[e]); cur[2 * e + 1] = pg8::bfhi(cv[e]); }
; #pragma unroll
;             for (int e = 0; e < 4; ++e) { o[2 * e] = pg8::bflo(gv[e]) * (w0[2 * e] * p2[2 * e] + w1[2 * e] * p1[2 * e] + w2[2 * e] * cur[2 * e]);
;                 o[2 * e + 1] = pg8::bfhi(gv[e]) * (w0[2 * e + 1] * p2[2 * e + 1] + w1[2 * e + 1] * p1[2 * e + 1] + w2[2 * e + 1] * cur[2 * e + 1]); }
;             v4u ov; ov.x = pk2(o[0], o[1]); ov.y = pk2(o[2], o[3]); ov.z = pk2(o[4], o[5]); ov.w = pk2(o[6], o[7]);
;             *(v4u*)(OAB + (size_t)m * 1024 + 512 + ch) = ov;
; #pragma unroll
;             for (int e = 0; e < 8; ++e) { p2[e] = p1[e]; p1[e] = cur[e]; }
	v_cvt_pk_bf16_f32 v30, v1, v26
	v_cvt_pk_bf16_f32 v31, v35, v31
	v_cvt_pk_bf16_f32 v32, v27, v32
	v_cvt_pk_bf16_f32 v33, v34, v33
	global_store_dwordx4 v[80:81], v[30:33], off offset:1024
	s_nop 0
	v_mov_b32_e32 v78, v45
	v_mov_b32_e32 v76, v47
	v_mov_b32_e32 v74, v49
	v_mov_b32_e32 v72, v51
	v_mov_b32_e32 v70, v53
	v_mov_b32_e32 v68, v29
	v_mov_b32_e32 v66, v55
	v_mov_b32_e32 v64, v57
	v_lshlrev_b32_e32 v79, 16, v108
	v_and_b32_e32 v77, 0xffff0000, v108
	v_lshlrev_b32_e32 v75, 16, v109
	v_and_b32_e32 v73, 0xffff0000, v109
	v_lshlrev_b32_e32 v71, 16, v110
	v_and_b32_e32 v69, 0xffff0000, v110
	v_lshlrev_b32_e32 v67, 16, v111
	v_and_b32_e32 v65, 0xffff0000, v111
	v_pk_mul_f32 v[82:83], v[14:15], v[78:79]
	v_pk_mul_f32 v[84:85], v[18:19], v[76:77]
	v_pk_mul_f32 v[86:87], v[16:17], v[74:75]
	v_pk_mul_f32 v[88:89], v[20:21], v[72:73]
	v_pk_mul_f32 v[90:91], v[10:11], v[70:71]
	v_pk_mul_f32 v[92:93], v[22:23], v[68:69]
	v_pk_mul_f32 v[94:95], v[12:13], v[66:67]
	v_pk_mul_f32 v[96:97], v[24:25], v[64:65]
	v_fma_f32 v43, v6, v44, v82
	v_fma_f32 v44, v7, v46, v84
	v_fma_f32 v46, v8, v48, v86
	v_fma_f32 v48, v9, v50, v88
	v_fma_f32 v50, v2, v52, v90
	v_fma_f32 v28, v3, v28, v92
	v_fma_f32 v52, v4, v54, v94
	v_fma_f32 v54, v5, v56, v96
	v_lshlrev_b32_e32 v1, 16, v112
	v_and_b32_e32 v27, 0xffff0000, v112
	v_lshlrev_b32_e32 v31, 16, v113
	v_and_b32_e32 v33, 0xffff0000, v113
	v_lshlrev_b32_e32 v35, 16, v114
	v_and_b32_e32 v39, 0xffff0000, v114
	v_lshlrev_b32_e32 v41, 16, v115
	v_and_b32_e32 v37, 0xffff0000, v115
	v_add_f32_e32 v43, v43, v83
	v_add_f32_e32 v44, v44, v85
	v_add_f32_e32 v46, v46, v87
	v_add_f32_e32 v48, v48, v89
	v_add_f32_e32 v50, v50, v91
	v_add_f32_e32 v28, v28, v93
	v_add_f32_e32 v52, v52, v95
	v_add_f32_e32 v54, v54, v97
	v_mul_f32_e32 v1, v43, v1
	v_mul_f32_e32 v27, v44, v27
	v_mul_f32_e32 v31, v46, v31
	v_mul_f32_e32 v33, v48, v33
	v_mul_f32_e32 v35, v50, v35
	v_mul_f32_e32 v28, v28, v39
	v_mul_f32_e32 v39, v52, v41
	v_mul_f32_e32 v37, v54, v37
	v_cvt_pk_bf16_f32 v82, v1, v27
	v_cvt_pk_bf16_f32 v83, v31, v33
	v_cvt_pk_bf16_f32 v84, v35, v28
	v_cvt_pk_bf16_f32 v85, v39, v37
	global_store_dwordx4 v[80:81], v[82:85], off offset:3072
	s_nop 0
	v_mov_b32_e32 v34, v79
	v_mov_b32_e32 v36, v77
	v_mov_b32_e32 v38, v75
	v_mov_b32_e32 v30, v73
	v_mov_b32_e32 v26, v71
	v_mov_b32_e32 v40, v69
	v_mov_b32_e32 v42, v67
	v_mov_b32_e32 v32, v65
	v_lshlrev_b32_e32 v35, 16, v116
	v_and_b32_e32 v37, 0xffff0000, v116
	v_lshlrev_b32_e32 v39, 16, v117
	v_and_b32_e32 v31, 0xffff0000, v117
	v_lshlrev_b32_e32 v27, 16, v118
	v_and_b32_e32 v41, 0xffff0000, v118
	v_lshlrev_b32_e32 v43, 16, v119
	v_and_b32_e32 v33, 0xffff0000, v119
	v_lshlrev_b32_e32 v1, 16, v120
	v_and_b32_e32 v28, 0xffff0000, v120
	v_lshlrev_b32_e32 v44, 16, v121
	v_and_b32_e32 v46, 0xffff0000, v121
	v_lshlrev_b32_e32 v48, 16, v122
	v_and_b32_e32 v50, 0xffff0000, v122
	v_lshlrev_b32_e32 v52, 16, v123
	v_and_b32_e32 v54, 0xffff0000, v123
	v_pk_mul_f32 v[80:81], v[14:15], v[34:35]
	v_pk_mul_f32 v[82:83], v[18:19], v[36:37]
	v_pk_mul_f32 v[84:85], v[16:17], v[38:39]
	v_pk_mul_f32 v[86:87], v[20:21], v[30:31]
	v_pk_mul_f32 v[88:89], v[10:11], v[26:27]
	v_pk_mul_f32 v[90:91], v[22:23], v[40:41]
	v_pk_mul_f32 v[92:93], v[12:13], v[42:43]
	v_pk_mul_f32 v[94:95], v[24:25], v[32:33]
	v_fma_f32 v26, v6, v45, v80
	v_fma_f32 v30, v7, v47, v82
	v_fma_f32 v32, v8, v49, v84
	v_fma_f32 v34, v9, v51, v86
	v_fma_f32 v36, v2, v53, v88
	v_fma_f32 v29, v3, v29, v90
	v_fma_f32 v38, v4, v55, v92
	v_fma_f32 v40, v5, v57, v94
	v_add_f32_e32 v26, v26, v81
	v_add_f32_e32 v30, v30, v83
	v_add_f32_e32 v32, v32, v85
	v_add_f32_e32 v34, v34, v87
	v_add_f32_e32 v36, v36, v89
	v_add_f32_e32 v29, v29, v91
	v_add_f32_e32 v38, v38, v93
	v_add_f32_e32 v40, v40, v95
	v_mul_f32_e32 v1, v26, v1
	v_mul_f32_e32 v26, v30, v28
	v_mul_f32_e32 v28, v32, v44
	v_mul_f32_e32 v30, v34, v46
	v_mul_f32_e32 v32, v36, v48
	v_mul_f32_e32 v29, v29, v50
	v_mul_f32_e32 v34, v38, v52
	v_mul_f32_e32 v36, v40, v54
	v_cvt_pk_bf16_f32 v44, v1, v26
	v_cvt_pk_bf16_f32 v45, v28, v30
	v_cvt_pk_bf16_f32 v46, v32, v29
	v_cvt_pk_bf16_f32 v47, v34, v36
	global_store_dwordx4 v[62:63], v[44:47], off offset:1024
	s_nop 0
	v_mov_b32_e32 v28, v35
	v_mov_b32_e32 v52, v37
	v_mov_b32_e32 v54, v39
	v_mov_b32_e32 v56, v31
	v_mov_b32_e32 v58, v27
	v_mov_b32_e32 v60, v41
	v_mov_b32_e32 v80, v43
	v_mov_b32_e32 v82, v33
	v_lshlrev_b32_e32 v29, 16, v124
	v_and_b32_e32 v53, 0xffff0000, v124
	v_lshlrev_b32_e32 v55, 16, v125
	v_and_b32_e32 v57, 0xffff0000, v125
	v_lshlrev_b32_e32 v59, 16, v126
	v_and_b32_e32 v61, 0xffff0000, v126
	v_lshlrev_b32_e32 v81, 16, v127
	v_and_b32_e32 v83, 0xffff0000, v127
	v_pk_mul_f32 v[84:85], v[14:15], v[28:29]
	v_pk_mul_f32 v[86:87], v[18:19], v[52:53]
	v_pk_mul_f32 v[88:89], v[16:17], v[54:55]
	v_pk_mul_f32 v[90:91], v[20:21], v[56:57]
	v_pk_mul_f32 v[92:93], v[10:11], v[58:59]
	v_pk_mul_f32 v[94:95], v[22:23], v[60:61]
	v_pk_mul_f32 v[96:97], v[12:13], v[80:81]
	v_pk_mul_f32 v[98:99], v[24:25], v[82:83]
	v_lshlrev_b32_e32 v1, 16, v128
	v_and_b32_e32 v26, 0xffff0000, v128
	v_lshlrev_b32_e32 v30, 16, v129
	v_and_b32_e32 v32, 0xffff0000, v129
	v_lshlrev_b32_e32 v38, 16, v131
	v_and_b32_e32 v40, 0xffff0000, v131
	v_mov_b32_e32 v44, v29
	v_mov_b32_e32 v46, v53
	v_mov_b32_e32 v48, v55
	v_fma_f32 v29, v6, v79, v84
	v_fma_f32 v42, v7, v77, v86
	v_fma_f32 v45, v8, v75, v88
	v_fma_f32 v47, v9, v73, v90
	v_fma_f32 v49, v2, v71, v92
	v_fma_f32 v51, v3, v69, v94
	v_fma_f32 v53, v4, v67, v96
	v_fma_f32 v55, v5, v65, v98
	v_lshlrev_b32_e32 v34, 16, v130
	v_and_b32_e32 v36, 0xffff0000, v130
	v_mov_b32_e32 v50, v57
	v_mov_b32_e32 v52, v59
	v_mov_b32_e32 v28, v61
; __device__ __forceinline__ unsigned pk2(float lo, float hi) { return pg8::cvt_pk_bf16(lo, hi); }
;     __device__ __forceinline__ void operator()(int item) const {
;     ...
;         for (int r = 0; r < 16; ++r) { const int m = m0 + r;
;             const v4u cv = *(const v4u*)(CUB + (size_t)m * CW + ch), gv = *(const v4u*)(GZB + (size_t)m * CW + ch);
;             float cur[8], o[8];
; #pragma unroll
;             for (int e = 0; e < 4; ++e) { cur[2 * e] = pg8::bflo(cv[e]); cur[2 * e + 1] = pg8::bfhi(cv[e]); }
; #pragma unroll
;             for (int e = 0; e < 4; ++e) { o[2 * e] = pg8::bflo(gv[e]) * (w0[2 * e] * p2[2 * e] + w1[2 * e] * p1[2 * e] + w2[2 * e] * cur[2 * e]);
;                 o[2 * e + 1] = pg8::bfhi(gv[e]) * (w0[2 * e + 1] * p2[2 * e + 1] + w1[2 * e + 1] * p1[2 * e + 1] + w2[2 * e + 1] * cur[2 * e + 1]); }
;             v4u ov; ov.x = pk2(o[0], o[1]); ov.y = pk2(o[2], o[3]); ov.z = pk2(o[4], o[5]); ov.w = pk2(o[6], o[7]);
;             *(v4u*)(OAB + (size_t)m * 1024 + 512 + ch) = ov;
; #pragma unroll
;             for (int e = 0; e < 8; ++e) { p2[e] = p1[e]; p1[e] = cur[e]; }
	v_mov_b32_e32 v54, v81
	v_mov_b32_e32 v56, v83
	v_add_f32_e32 v29, v29, v85
	v_add_f32_e32 v42, v42, v87
	v_add_f32_e32 v45, v45, v89
	v_add_f32_e32 v47, v47, v91
	v_add_f32_e32 v49, v49, v93
	v_add_f32_e32 v51, v51, v95
	v_add_f32_e32 v53, v53, v97
	v_add_f32_e32 v55, v55, v99
	v_mul_f32_e32 v1, v29, v1
	v_mul_f32_e32 v26, v42, v26
	v_mul_f32_e32 v29, v45, v30
	v_mul_f32_e32 v30, v47, v32
	v_mul_f32_e32 v32, v49, v34
	v_mul_f32_e32 v34, v51, v36
	v_mul_f32_e32 v36, v53, v38
	v_mul_f32_e32 v38, v55, v40
	v_cvt_pk_bf16_f32 v58, v1, v26
	v_cvt_pk_bf16_f32 v59, v29, v30
	v_cvt_pk_bf16_f32 v60, v32, v34
	v_cvt_pk_bf16_f32 v61, v36, v38
	global_store_dwordx4 v[62:63], v[58:61], off offset:3072
	s_mov_b32 s84, 0x3000
	s_mov_b32 s85, 0
	v_lshl_add_u64 v[230:231], v[242:243], 0, s[84:85]
	v_add_co_u32_e32 v226, vcc, s59, v230
	s_nop 1
	v_addc_co_u32_e32 v227, vcc, 0, v231, vcc
	v_add_co_u32_e32 v228, vcc, s60, v230
	s_nop 1
	v_addc_co_u32_e32 v229, vcc, 0, v231, vcc
	global_load_dwordx4 v[100:103], v[226:227], off offset:0
	global_load_dwordx4 v[104:107], v[228:229], off offset:0
	global_load_dwordx4 v[108:111], v[226:227], off offset:1024
	global_load_dwordx4 v[112:115], v[228:229], off offset:1024
	global_load_dwordx4 v[116:119], v[226:227], off offset:2048
	global_load_dwordx4 v[120:123], v[228:229], off offset:2048
	global_load_dwordx4 v[124:127], v[226:227], off offset:3072
	global_load_dwordx4 v[128:131], v[228:229], off offset:3072
	s_waitcnt vmcnt(20)
	s_nop 0
	v_lshl_add_u64 v[60:61], s[10:11], 0, v[210:211]
	v_add_co_u32_e32 v58, vcc, s59, v60
	v_lshl_add_u64 v[62:63], s[8:9], 0, v[210:211]
	s_nop 0
	v_addc_co_u32_e32 v59, vcc, 0, v61, vcc
	v_add_co_u32_e32 v60, vcc, s60, v60
	s_add_u32 s8, s8, 0x2000
	s_nop 0
	v_addc_co_u32_e32 v61, vcc, 0, v61, vcc
	v_add_co_u32_e32 v80, vcc, s61, v62
	s_addc_u32 s9, s9, 0
	s_nop 0
	v_addc_co_u32_e32 v81, vcc, 0, v63, vcc
	v_add_co_u32_e32 v62, vcc, s62, v62
	s_add_u32 s10, s10, 0x1000
	s_nop 0
	v_addc_co_u32_e32 v63, vcc, 0, v63, vcc
	s_addc_u32 s11, s11, 0
	s_add_i32 s43, s43, -4
	s_cmp_lg_u32 s43, 0
	v_and_b32_e32 v51, 0xffff0000, v133
	v_and_b32_e32 v29, 0xffff0000, v134
	v_and_b32_e32 v57, 0xffff0000, v135
	v_lshlrev_b32_e32 v45, 16, v132
	v_and_b32_e32 v47, 0xffff0000, v132
	v_lshlrev_b32_e32 v49, 16, v133
	v_lshlrev_b32_e32 v53, 16, v134
	v_lshlrev_b32_e32 v55, 16, v135
	v_pk_mul_f32 v[88:89], v[20:21], v[50:51]
	v_pk_mul_f32 v[92:93], v[22:23], v[28:29]
	v_pk_mul_f32 v[96:97], v[24:25], v[56:57]
	v_pk_mul_f32 v[82:83], v[14:15], v[44:45]
	v_pk_mul_f32 v[84:85], v[18:19], v[46:47]
	v_pk_mul_f32 v[86:87], v[16:17], v[48:49]
	v_pk_mul_f32 v[90:91], v[10:11], v[52:53]
	v_pk_mul_f32 v[94:95], v[12:13], v[54:55]
	v_fma_f32 v31, v9, v31, v88
	v_fma_f32 v41, v3, v41, v92
	v_fma_f32 v33, v5, v33, v96
	v_and_b32_e32 v32, 0xffff0000, v137
	v_and_b32_e32 v36, 0xffff0000, v138
	v_and_b32_e32 v40, 0xffff0000, v139
	v_fma_f32 v35, v6, v35, v82
	v_fma_f32 v37, v7, v37, v84
	v_fma_f32 v39, v8, v39, v86
	v_fma_f32 v27, v2, v27, v90
	v_fma_f32 v42, v4, v43, v94
	v_add_f32_e32 v31, v31, v89
	v_add_f32_e32 v41, v41, v93
	v_add_f32_e32 v33, v33, v97
	v_lshlrev_b32_e32 v1, 16, v136
	v_and_b32_e32 v26, 0xffff0000, v136
	v_lshlrev_b32_e32 v30, 16, v137
	v_lshlrev_b32_e32 v34, 16, v138
	v_lshlrev_b32_e32 v38, 16, v139
	v_add_f32_e32 v35, v35, v83
	v_add_f32_e32 v37, v37, v85
	v_add_f32_e32 v39, v39, v87
	v_add_f32_e32 v27, v27, v91
	v_add_f32_e32 v42, v42, v95
	v_mul_f32_e32 v31, v31, v32
	v_mul_f32_e32 v32, v41, v36
	v_mul_f32_e32 v33, v33, v40
	v_mul_f32_e32 v1, v35, v1
	v_mul_f32_e32 v26, v37, v26
	v_mul_f32_e32 v35, v39, v30
	v_mul_f32_e32 v27, v27, v34
	v_mul_f32_e32 v34, v42, v38
	v_cvt_pk_bf16_f32 v30, v1, v26
	v_cvt_pk_bf16_f32 v31, v35, v31
	v_cvt_pk_bf16_f32 v32, v27, v32
	v_cvt_pk_bf16_f32 v33, v34, v33
	global_store_dwordx4 v[80:81], v[30:33], off offset:1024
	s_nop 0
	v_mov_b32_e32 v78, v45
	v_mov_b32_e32 v76, v47
	v_mov_b32_e32 v74, v49
	v_mov_b32_e32 v72, v51
	v_mov_b32_e32 v70, v53
	v_mov_b32_e32 v68, v29
	v_mov_b32_e32 v66, v55
	v_mov_b32_e32 v64, v57
	v_lshlrev_b32_e32 v79, 16, v140
	v_and_b32_e32 v77, 0xffff0000, v140
	v_lshlrev_b32_e32 v75, 16, v141
	v_and_b32_e32 v73, 0xffff0000, v141
	v_lshlrev_b32_e32 v71, 16, v142
	v_and_b32_e32 v69, 0xffff0000, v142
	v_lshlrev_b32_e32 v67, 16, v143
	v_and_b32_e32 v65, 0xffff0000, v143
	v_pk_mul_f32 v[82:83], v[14:15], v[78:79]
	v_pk_mul_f32 v[84:85], v[18:19], v[76:77]
	v_pk_mul_f32 v[86:87], v[16:17], v[74:75]
	v_pk_mul_f32 v[88:89], v[20:21], v[72:73]
	v_pk_mul_f32 v[90:91], v[10:11], v[70:71]
	v_pk_mul_f32 v[92:93], v[22:23], v[68:69]
	v_pk_mul_f32 v[94:95], v[12:13], v[66:67]
	v_pk_mul_f32 v[96:97], v[24:25], v[64:65]
	v_fma_f32 v43, v6, v44, v82
	v_fma_f32 v44, v7, v46, v84
	v_fma_f32 v46, v8, v48, v86
	v_fma_f32 v48, v9, v50, v88
	v_fma_f32 v50, v2, v52, v90
	v_fma_f32 v28, v3, v28, v92
	v_fma_f32 v52, v4, v54, v94
	v_fma_f32 v54, v5, v56, v96
	v_lshlrev_b32_e32 v1, 16, v144
	v_and_b32_e32 v27, 0xffff0000, v144
	v_lshlrev_b32_e32 v31, 16, v145
	v_and_b32_e32 v33, 0xffff0000, v145
	v_lshlrev_b32_e32 v35, 16, v146
	v_and_b32_e32 v39, 0xffff0000, v146
	v_lshlrev_b32_e32 v41, 16, v147
	v_and_b32_e32 v37, 0xffff0000, v147
	v_add_f32_e32 v43, v43, v83
	v_add_f32_e32 v44, v44, v85
	v_add_f32_e32 v46, v46, v87
	v_add_f32_e32 v48, v48, v89
	v_add_f32_e32 v50, v50, v91
	v_add_f32_e32 v28, v28, v93
	v_add_f32_e32 v52, v52, v95
	v_add_f32_e32 v54, v54, v97
	v_mul_f32_e32 v1, v43, v1
	v_mul_f32_e32 v27, v44, v27
	v_mul_f32_e32 v31, v46, v31
	v_mul_f32_e32 v33, v48, v33
	v_mul_f32_e32 v35, v50, v35
	v_mul_f32_e32 v28, v28, v39
	v_mul_f32_e32 v39, v52, v41
; __device__ __forceinline__ unsigned pk2(float lo, float hi) { return pg8::cvt_pk_bf16(lo, hi); }
;     __device__ __forceinline__ void operator()(int item) const {
;     ...
;         for (int r = 0; r < 16; ++r) { const int m = m0 + r;
;             const v4u cv = *(const v4u*)(CUB + (size_t)m * CW + ch), gv = *(const v4u*)(GZB + (size_t)m * CW + ch);
;             float cur[8], o[8];
; #pragma unroll
;             for (int e = 0; e < 4; ++e) { cur[2 * e] = pg8::bflo(cv[e]); cur[2 * e + 1] = pg8::bfhi(cv[e]); }
; #pragma unroll
;             for (int e = 0; e < 4; ++e) { o[2 * e] = pg8::bflo(gv[e]) * (w0[2 * e] * p2[2 * e] + w1[2 * e] * p1[2 * e] + w2[2 * e] * cur[2 * e]);
;                 o[2 * e + 1] = pg8::bfhi(gv[e]) * (w0[2 * e + 1] * p2[2 * e + 1] + w1[2 * e + 1] * p1[2 * e + 1] + w2[2 * e + 1] * cur[2 * e + 1]); }
;             v4u ov; ov.x = pk2(o[0], o[1]); ov.y = pk2(o[2], o[3]); ov.z = pk2(o[4], o[5]); ov.w = pk2(o[6], o[7]);
;             *(v4u*)(OAB + (size_t)m * 1024 + 512 + ch) = ov;
; #pragma unroll
;             for (int e = 0; e < 8; ++e) { p2[e] = p1[e]; p1[e] = cur[e]; }
	v_mul_f32_e32 v37, v54, v37
	v_cvt_pk_bf16_f32 v82, v1, v27
	v_cvt_pk_bf16_f32 v83, v31, v33
	v_cvt_pk_bf16_f32 v84, v35, v28
	v_cvt_pk_bf16_f32 v85, v39, v37
	global_store_dwordx4 v[80:81], v[82:85], off offset:3072
	s_nop 0
	v_mov_b32_e32 v34, v79
	v_mov_b32_e32 v36, v77
	v_mov_b32_e32 v38, v75
	v_mov_b32_e32 v30, v73
	v_mov_b32_e32 v26, v71
	v_mov_b32_e32 v40, v69
	v_mov_b32_e32 v42, v67
	v_mov_b32_e32 v32, v65
	v_lshlrev_b32_e32 v35, 16, v148
	v_and_b32_e32 v37, 0xffff0000, v148
	v_lshlrev_b32_e32 v39, 16, v149
	v_and_b32_e32 v31, 0xffff0000, v149
	v_lshlrev_b32_e32 v27, 16, v150
	v_and_b32_e32 v41, 0xffff0000, v150
	v_lshlrev_b32_e32 v43, 16, v151
	v_and_b32_e32 v33, 0xffff0000, v151
	v_lshlrev_b32_e32 v1, 16, v152
	v_and_b32_e32 v28, 0xffff0000, v152
	v_lshlrev_b32_e32 v44, 16, v153
	v_and_b32_e32 v46, 0xffff0000, v153
	v_lshlrev_b32_e32 v48, 16, v154
	v_and_b32_e32 v50, 0xffff0000, v154
	v_lshlrev_b32_e32 v52, 16, v155
	v_and_b32_e32 v54, 0xffff0000, v155
	v_pk_mul_f32 v[80:81], v[14:15], v[34:35]
	v_pk_mul_f32 v[82:83], v[18:19], v[36:37]
	v_pk_mul_f32 v[84:85], v[16:17], v[38:39]
	v_pk_mul_f32 v[86:87], v[20:21], v[30:31]
	v_pk_mul_f32 v[88:89], v[10:11], v[26:27]
	v_pk_mul_f32 v[90:91], v[22:23], v[40:41]
	v_pk_mul_f32 v[92:93], v[12:13], v[42:43]
	v_pk_mul_f32 v[94:95], v[24:25], v[32:33]
	v_fma_f32 v26, v6, v45, v80
	v_fma_f32 v30, v7, v47, v82
	v_fma_f32 v32, v8, v49, v84
	v_fma_f32 v34, v9, v51, v86
	v_fma_f32 v36, v2, v53, v88
	v_fma_f32 v29, v3, v29, v90
	v_fma_f32 v38, v4, v55, v92
	v_fma_f32 v40, v5, v57, v94
	v_add_f32_e32 v26, v26, v81
	v_add_f32_e32 v30, v30, v83
	v_add_f32_e32 v32, v32, v85
	v_add_f32_e32 v34, v34, v87
	v_add_f32_e32 v36, v36, v89
	v_add_f32_e32 v29, v29, v91
	v_add_f32_e32 v38, v38, v93
	v_add_f32_e32 v40, v40, v95
	v_mul_f32_e32 v1, v26, v1
	v_mul_f32_e32 v26, v30, v28
	v_mul_f32_e32 v28, v32, v44
	v_mul_f32_e32 v30, v34, v46
	v_mul_f32_e32 v32, v36, v48
	v_mul_f32_e32 v29, v29, v50
	v_mul_f32_e32 v34, v38, v52
	v_mul_f32_e32 v36, v40, v54
	v_cvt_pk_bf16_f32 v44, v1, v26
	v_cvt_pk_bf16_f32 v45, v28, v30
	v_cvt_pk_bf16_f32 v46, v32, v29
	v_cvt_pk_bf16_f32 v47, v34, v36
	global_store_dwordx4 v[62:63], v[44:47], off offset:1024
	s_nop 0
	v_mov_b32_e32 v28, v35
	v_mov_b32_e32 v52, v37
	v_mov_b32_e32 v54, v39
	v_mov_b32_e32 v56, v31
	v_mov_b32_e32 v58, v27
	v_mov_b32_e32 v60, v41
	v_mov_b32_e32 v80, v43
	v_mov_b32_e32 v82, v33
	v_lshlrev_b32_e32 v29, 16, v156
	v_and_b32_e32 v53, 0xffff0000, v156
	v_lshlrev_b32_e32 v55, 16, v157
	v_and_b32_e32 v57, 0xffff0000, v157
	v_lshlrev_b32_e32 v59, 16, v158
	v_and_b32_e32 v61, 0xffff0000, v158
	v_lshlrev_b32_e32 v81, 16, v159
	v_and_b32_e32 v83, 0xffff0000, v159
	v_pk_mul_f32 v[84:85], v[14:15], v[28:29]
	v_pk_mul_f32 v[86:87], v[18:19], v[52:53]
	v_pk_mul_f32 v[88:89], v[16:17], v[54:55]
	v_pk_mul_f32 v[90:91], v[20:21], v[56:57]
	v_pk_mul_f32 v[92:93], v[10:11], v[58:59]
	v_pk_mul_f32 v[94:95], v[22:23], v[60:61]
	v_pk_mul_f32 v[96:97], v[12:13], v[80:81]
	v_pk_mul_f32 v[98:99], v[24:25], v[82:83]
	v_lshlrev_b32_e32 v1, 16, v160
	v_and_b32_e32 v26, 0xffff0000, v160
	v_lshlrev_b32_e32 v30, 16, v161
	v_and_b32_e32 v32, 0xffff0000, v161
	v_lshlrev_b32_e32 v38, 16, v163
	v_and_b32_e32 v40, 0xffff0000, v163
	v_mov_b32_e32 v44, v29
	v_mov_b32_e32 v46, v53
	v_mov_b32_e32 v48, v55
	v_fma_f32 v29, v6, v79, v84
	v_fma_f32 v42, v7, v77, v86
	v_fma_f32 v45, v8, v75, v88
	v_fma_f32 v47, v9, v73, v90
	v_fma_f32 v49, v2, v71, v92
	v_fma_f32 v51, v3, v69, v94
	v_fma_f32 v53, v4, v67, v96
	v_fma_f32 v55, v5, v65, v98
	v_lshlrev_b32_e32 v34, 16, v162
	v_and_b32_e32 v36, 0xffff0000, v162
	v_mov_b32_e32 v50, v57
	v_mov_b32_e32 v52, v59
	v_mov_b32_e32 v28, v61
	v_mov_b32_e32 v54, v81
	v_mov_b32_e32 v56, v83
	v_add_f32_e32 v29, v29, v85
	v_add_f32_e32 v42, v42, v87
	v_add_f32_e32 v45, v45, v89
	v_add_f32_e32 v47, v47, v91
	v_add_f32_e32 v49, v49, v93
	v_add_f32_e32 v51, v51, v95
	v_add_f32_e32 v53, v53, v97
	v_add_f32_e32 v55, v55, v99
	v_mul_f32_e32 v1, v29, v1
	v_mul_f32_e32 v26, v42, v26
	v_mul_f32_e32 v29, v45, v30
	v_mul_f32_e32 v30, v47, v32
	v_mul_f32_e32 v32, v49, v34
	v_mul_f32_e32 v34, v51, v36
	v_mul_f32_e32 v36, v53, v38
	v_mul_f32_e32 v38, v55, v40
	v_cvt_pk_bf16_f32 v58, v1, v26
	v_cvt_pk_bf16_f32 v59, v29, v30
	v_cvt_pk_bf16_f32 v60, v32, v34
	v_cvt_pk_bf16_f32 v61, v36, v38
	global_store_dwordx4 v[62:63], v[58:61], off offset:3072
	s_waitcnt vmcnt(16)
; __device__ __forceinline__ unsigned pk2(float lo, float hi) { return pg8::cvt_pk_bf16(lo, hi); }
;     __device__ __forceinline__ void operator()(int item) const {
;     ...
;         for (int r = 0; r < 16; ++r) { const int m = m0 + r;
;             const v4u cv = *(const v4u*)(CUB + (size_t)m * CW + ch), gv = *(const v4u*)(GZB + (size_t)m * CW + ch);
;             float cur[8], o[8];
; #pragma unroll
;             for (int e = 0; e < 4; ++e) { cur[2 * e] = pg8::bflo(cv[e]); cur[2 * e + 1] = pg8::bfhi(cv[e]); }
; #pragma unroll
;             for (int e = 0; e < 4; ++e) { o[2 * e] = pg8::bflo(gv[e]) * (w0[2 * e] * p2[2 * e] + w1[2 * e] * p1[2 * e] + w2[2 * e] * cur[2 * e]);
;                 o[2 * e + 1] = pg8::bfhi(gv[e]) * (w0[2 * e + 1] * p2[2 * e + 1] + w1[2 * e + 1] * p1[2 * e + 1] + w2[2 * e + 1] * cur[2 * e + 1]); }
;             v4u ov; ov.x = pk2(o[0], o[1]); ov.y = pk2(o[2], o[3]); ov.z = pk2(o[4], o[5]); ov.w = pk2(o[6], o[7]);
;             *(v4u*)(OAB + (size_t)m * 1024 + 512 + ch) = ov;
; #pragma unroll
;             for (int e = 0; e < 8; ++e) { p2[e] = p1[e]; p1[e] = cur[e]; }
	s_nop 0
	v_lshl_add_u64 v[60:61], s[10:11], 0, v[210:211]
	v_add_co_u32_e32 v58, vcc, s59, v60
	v_lshl_add_u64 v[62:63], s[8:9], 0, v[210:211]
	s_nop 0
	v_addc_co_u32_e32 v59, vcc, 0, v61, vcc
	v_add_co_u32_e32 v60, vcc, s60, v60
	s_add_u32 s8, s8, 0x2000
	s_nop 0
	v_addc_co_u32_e32 v61, vcc, 0, v61, vcc
	v_add_co_u32_e32 v80, vcc, s61, v62
	s_addc_u32 s9, s9, 0
	s_nop 0
	v_addc_co_u32_e32 v81, vcc, 0, v63, vcc
	v_add_co_u32_e32 v62, vcc, s62, v62
	s_add_u32 s10, s10, 0x1000
	s_nop 0
	v_addc_co_u32_e32 v63, vcc, 0, v63, vcc
	s_addc_u32 s11, s11, 0
	s_add_i32 s43, s43, -4
	s_cmp_lg_u32 s43, 0
	v_and_b32_e32 v51, 0xffff0000, v165
	v_and_b32_e32 v29, 0xffff0000, v166
	v_and_b32_e32 v57, 0xffff0000, v167
	v_lshlrev_b32_e32 v45, 16, v164
	v_and_b32_e32 v47, 0xffff0000, v164
	v_lshlrev_b32_e32 v49, 16, v165
	v_lshlrev_b32_e32 v53, 16, v166
	v_lshlrev_b32_e32 v55, 16, v167
	v_pk_mul_f32 v[88:89], v[20:21], v[50:51]
	v_pk_mul_f32 v[92:93], v[22:23], v[28:29]
	v_pk_mul_f32 v[96:97], v[24:25], v[56:57]
	v_pk_mul_f32 v[82:83], v[14:15], v[44:45]
	v_pk_mul_f32 v[84:85], v[18:19], v[46:47]
	v_pk_mul_f32 v[86:87], v[16:17], v[48:49]
	v_pk_mul_f32 v[90:91], v[10:11], v[52:53]
	v_pk_mul_f32 v[94:95], v[12:13], v[54:55]
	v_fma_f32 v31, v9, v31, v88
	v_fma_f32 v41, v3, v41, v92
	v_fma_f32 v33, v5, v33, v96
	v_and_b32_e32 v32, 0xffff0000, v169
	v_and_b32_e32 v36, 0xffff0000, v170
	v_and_b32_e32 v40, 0xffff0000, v171
	v_fma_f32 v35, v6, v35, v82
	v_fma_f32 v37, v7, v37, v84
	v_fma_f32 v39, v8, v39, v86
	v_fma_f32 v27, v2, v27, v90
	v_fma_f32 v42, v4, v43, v94
	v_add_f32_e32 v31, v31, v89
	v_add_f32_e32 v41, v41, v93
	v_add_f32_e32 v33, v33, v97
	v_lshlrev_b32_e32 v1, 16, v168
	v_and_b32_e32 v26, 0xffff0000, v168
	v_lshlrev_b32_e32 v30, 16, v169
	v_lshlrev_b32_e32 v34, 16, v170
	v_lshlrev_b32_e32 v38, 16, v171
	v_add_f32_e32 v35, v35, v83
	v_add_f32_e32 v37, v37, v85
	v_add_f32_e32 v39, v39, v87
	v_add_f32_e32 v27, v27, v91
	v_add_f32_e32 v42, v42, v95
	v_mul_f32_e32 v31, v31, v32
	v_mul_f32_e32 v32, v41, v36
	v_mul_f32_e32 v33, v33, v40
	v_mul_f32_e32 v1, v35, v1
	v_mul_f32_e32 v26, v37, v26
	v_mul_f32_e32 v35, v39, v30
	v_mul_f32_e32 v27, v27, v34
	v_mul_f32_e32 v34, v42, v38
	v_cvt_pk_bf16_f32 v30, v1, v26
	v_cvt_pk_bf16_f32 v31, v35, v31
	v_cvt_pk_bf16_f32 v32, v27, v32
	v_cvt_pk_bf16_f32 v33, v34, v33
	global_store_dwordx4 v[80:81], v[30:33], off offset:1024
	s_nop 0
	v_mov_b32_e32 v78, v45
	v_mov_b32_e32 v76, v47
	v_mov_b32_e32 v74, v49
	v_mov_b32_e32 v72, v51
	v_mov_b32_e32 v70, v53
	v_mov_b32_e32 v68, v29
	v_mov_b32_e32 v66, v55
	v_mov_b32_e32 v64, v57
	v_lshlrev_b32_e32 v79, 16, v172
	v_and_b32_e32 v77, 0xffff0000, v172
	v_lshlrev_b32_e32 v75, 16, v173
	v_and_b32_e32 v73, 0xffff0000, v173
	v_lshlrev_b32_e32 v71, 16, v174
	v_and_b32_e32 v69, 0xffff0000, v174
	v_lshlrev_b32_e32 v67, 16, v175
	v_and_b32_e32 v65, 0xffff0000, v175
	v_pk_mul_f32 v[82:83], v[14:15], v[78:79]
	v_pk_mul_f32 v[84:85], v[18:19], v[76:77]
	v_pk_mul_f32 v[86:87], v[16:17], v[74:75]
	v_pk_mul_f32 v[88:89], v[20:21], v[72:73]
	v_pk_mul_f32 v[90:91], v[10:11], v[70:71]
	v_pk_mul_f32 v[92:93], v[22:23], v[68:69]
	v_pk_mul_f32 v[94:95], v[12:13], v[66:67]
	v_pk_mul_f32 v[96:97], v[24:25], v[64:65]
	v_fma_f32 v43, v6, v44, v82
	v_fma_f32 v44, v7, v46, v84
	v_fma_f32 v46, v8, v48, v86
	v_fma_f32 v48, v9, v50, v88
	v_fma_f32 v50, v2, v52, v90
	v_fma_f32 v28, v3, v28, v92
	v_fma_f32 v52, v4, v54, v94
	v_fma_f32 v54, v5, v56, v96
	v_lshlrev_b32_e32 v1, 16, v176
	v_and_b32_e32 v27, 0xffff0000, v176
	v_lshlrev_b32_e32 v31, 16, v177
	v_and_b32_e32 v33, 0xffff0000, v177
	v_lshlrev_b32_e32 v35, 16, v178
	v_and_b32_e32 v39, 0xffff0000, v178
	v_lshlrev_b32_e32 v41, 16, v179
	v_and_b32_e32 v37, 0xffff0000, v179
	v_add_f32_e32 v43, v43, v83
	v_add_f32_e32 v44, v44, v85
	v_add_f32_e32 v46, v46, v87
	v_add_f32_e32 v48, v48, v89
	v_add_f32_e32 v50, v50, v91
	v_add_f32_e32 v28, v28, v93
	v_add_f32_e32 v52, v52, v95
	v_add_f32_e32 v54, v54, v97
	v_mul_f32_e32 v1, v43, v1
	v_mul_f32_e32 v27, v44, v27
	v_mul_f32_e32 v31, v46, v31
	v_mul_f32_e32 v33, v48, v33
	v_mul_f32_e32 v35, v50, v35
	v_mul_f32_e32 v28, v28, v39
	v_mul_f32_e32 v39, v52, v41
	v_mul_f32_e32 v37, v54, v37
	v_cvt_pk_bf16_f32 v82, v1, v27
	v_cvt_pk_bf16_f32 v83, v31, v33
	v_cvt_pk_bf16_f32 v84, v35, v28
	v_cvt_pk_bf16_f32 v85, v39, v37
	global_store_dwordx4 v[80:81], v[82:85], off offset:3072
	s_nop 0
	v_mov_b32_e32 v34, v79
	v_mov_b32_e32 v36, v77
	v_mov_b32_e32 v38, v75
	v_mov_b32_e32 v30, v73
	v_mov_b32_e32 v26, v71
	v_mov_b32_e32 v40, v69
	v_mov_b32_e32 v42, v67
	v_mov_b32_e32 v32, v65
	v_lshlrev_b32_e32 v35, 16, v180
	v_and_b32_e32 v37, 0xffff0000, v180
	v_lshlrev_b32_e32 v39, 16, v181
	v_and_b32_e32 v31, 0xffff0000, v181
	v_lshlrev_b32_e32 v27, 16, v182
	v_and_b32_e32 v41, 0xffff0000, v182
	v_lshlrev_b32_e32 v43, 16, v183
	v_and_b32_e32 v33, 0xffff0000, v183
	v_lshlrev_b32_e32 v1, 16, v184
	v_and_b32_e32 v28, 0xffff0000, v184
	v_lshlrev_b32_e32 v44, 16, v185
	v_and_b32_e32 v46, 0xffff0000, v185
	v_lshlrev_b32_e32 v48, 16, v186
	v_and_b32_e32 v50, 0xffff0000, v186
	v_lshlrev_b32_e32 v52, 16, v187
	v_and_b32_e32 v54, 0xffff0000, v187
	v_pk_mul_f32 v[80:81], v[14:15], v[34:35]
	v_pk_mul_f32 v[82:83], v[18:19], v[36:37]
	v_pk_mul_f32 v[84:85], v[16:17], v[38:39]
	v_pk_mul_f32 v[86:87], v[20:21], v[30:31]
	v_pk_mul_f32 v[88:89], v[10:11], v[26:27]
	v_pk_mul_f32 v[90:91], v[22:23], v[40:41]
	v_pk_mul_f32 v[92:93], v[12:13], v[42:43]
	v_pk_mul_f32 v[94:95], v[24:25], v[32:33]
	v_fma_f32 v26, v6, v45, v80
	v_fma_f32 v30, v7, v47, v82
	v_fma_f32 v32, v8, v49, v84
	v_fma_f32 v34, v9, v51, v86
	v_fma_f32 v36, v2, v53, v88
	v_fma_f32 v29, v3, v29, v90
; __device__ __forceinline__ unsigned pk2(float lo, float hi) { return pg8::cvt_pk_bf16(lo, hi); }
;     __device__ __forceinline__ void operator()(int item) const {
;     ...
;         for (int r = 0; r < 16; ++r) { const int m = m0 + r;
;             const v4u cv = *(const v4u*)(CUB + (size_t)m * CW + ch), gv = *(const v4u*)(GZB + (size_t)m * CW + ch);
;             float cur[8], o[8];
; #pragma unroll
;             for (int e = 0; e < 4; ++e) { cur[2 * e] = pg8::bflo(cv[e]); cur[2 * e + 1] = pg8::bfhi(cv[e]); }
; #pragma unroll
;             for (int e = 0; e < 4; ++e) { o[2 * e] = pg8::bflo(gv[e]) * (w0[2 * e] * p2[2 * e] + w1[2 * e] * p1[2 * e] + w2[2 * e] * cur[2 * e]);
;                 o[2 * e + 1] = pg8::bfhi(gv[e]) * (w0[2 * e + 1] * p2[2 * e + 1] + w1[2 * e + 1] * p1[2 * e + 1] + w2[2 * e + 1] * cur[2 * e + 1]); }
;             v4u ov; ov.x = pk2(o[0], o[1]); ov.y = pk2(o[2], o[3]); ov.z = pk2(o[4], o[5]); ov.w = pk2(o[6], o[7]);
;             *(v4u*)(OAB + (size_t)m * 1024 + 512 + ch) = ov;
; #pragma unroll
;             for (int e = 0; e < 8; ++e) { p2[e] = p1[e]; p1[e] = cur[e]; }
	v_fma_f32 v38, v4, v55, v92
	v_fma_f32 v40, v5, v57, v94
	v_add_f32_e32 v26, v26, v81
	v_add_f32_e32 v30, v30, v83
	v_add_f32_e32 v32, v32, v85
	v_add_f32_e32 v34, v34, v87
	v_add_f32_e32 v36, v36, v89
	v_add_f32_e32 v29, v29, v91
	v_add_f32_e32 v38, v38, v93
	v_add_f32_e32 v40, v40, v95
	v_mul_f32_e32 v1, v26, v1
	v_mul_f32_e32 v26, v30, v28
	v_mul_f32_e32 v28, v32, v44
	v_mul_f32_e32 v30, v34, v46
	v_mul_f32_e32 v32, v36, v48
	v_mul_f32_e32 v29, v29, v50
	v_mul_f32_e32 v34, v38, v52
	v_mul_f32_e32 v36, v40, v54
	v_cvt_pk_bf16_f32 v44, v1, v26
	v_cvt_pk_bf16_f32 v45, v28, v30
	v_cvt_pk_bf16_f32 v46, v32, v29
	v_cvt_pk_bf16_f32 v47, v34, v36
	global_store_dwordx4 v[62:63], v[44:47], off offset:1024
	s_nop 0
	v_mov_b32_e32 v28, v35
	v_mov_b32_e32 v52, v37
	v_mov_b32_e32 v54, v39
	v_mov_b32_e32 v56, v31
	v_mov_b32_e32 v58, v27
	v_mov_b32_e32 v60, v41
	v_mov_b32_e32 v80, v43
	v_mov_b32_e32 v82, v33
	v_lshlrev_b32_e32 v29, 16, v188
	v_and_b32_e32 v53, 0xffff0000, v188
	v_lshlrev_b32_e32 v55, 16, v189
	v_and_b32_e32 v57, 0xffff0000, v189
	v_lshlrev_b32_e32 v59, 16, v190
	v_and_b32_e32 v61, 0xffff0000, v190
	v_lshlrev_b32_e32 v81, 16, v191
	v_and_b32_e32 v83, 0xffff0000, v191
	v_pk_mul_f32 v[84:85], v[14:15], v[28:29]
	v_pk_mul_f32 v[86:87], v[18:19], v[52:53]
	v_pk_mul_f32 v[88:89], v[16:17], v[54:55]
	v_pk_mul_f32 v[90:91], v[20:21], v[56:57]
	v_pk_mul_f32 v[92:93], v[10:11], v[58:59]
	v_pk_mul_f32 v[94:95], v[22:23], v[60:61]
	v_pk_mul_f32 v[96:97], v[12:13], v[80:81]
	v_pk_mul_f32 v[98:99], v[24:25], v[82:83]
	v_lshlrev_b32_e32 v1, 16, v192
	v_and_b32_e32 v26, 0xffff0000, v192
	v_lshlrev_b32_e32 v30, 16, v193
	v_and_b32_e32 v32, 0xffff0000, v193
	v_lshlrev_b32_e32 v38, 16, v195
	v_and_b32_e32 v40, 0xffff0000, v195
	v_mov_b32_e32 v44, v29
	v_mov_b32_e32 v46, v53
	v_mov_b32_e32 v48, v55
	v_fma_f32 v29, v6, v79, v84
	v_fma_f32 v42, v7, v77, v86
	v_fma_f32 v45, v8, v75, v88
	v_fma_f32 v47, v9, v73, v90
	v_fma_f32 v49, v2, v71, v92
	v_fma_f32 v51, v3, v69, v94
	v_fma_f32 v53, v4, v67, v96
	v_fma_f32 v55, v5, v65, v98
	v_lshlrev_b32_e32 v34, 16, v194
	v_and_b32_e32 v36, 0xffff0000, v194
	v_mov_b32_e32 v50, v57
	v_mov_b32_e32 v52, v59
	v_mov_b32_e32 v28, v61
	v_mov_b32_e32 v54, v81
	v_mov_b32_e32 v56, v83
	v_add_f32_e32 v29, v29, v85
	v_add_f32_e32 v42, v42, v87
	v_add_f32_e32 v45, v45, v89
	v_add_f32_e32 v47, v47, v91
	v_add_f32_e32 v49, v49, v93
	v_add_f32_e32 v51, v51, v95
	v_add_f32_e32 v53, v53, v97
	v_add_f32_e32 v55, v55, v99
	v_mul_f32_e32 v1, v29, v1
	v_mul_f32_e32 v26, v42, v26
	v_mul_f32_e32 v29, v45, v30
	v_mul_f32_e32 v30, v47, v32
	v_mul_f32_e32 v32, v49, v34
	v_mul_f32_e32 v34, v51, v36
	v_mul_f32_e32 v36, v53, v38
	v_mul_f32_e32 v38, v55, v40
	v_cvt_pk_bf16_f32 v58, v1, v26
	v_cvt_pk_bf16_f32 v59, v29, v30
	v_cvt_pk_bf16_f32 v60, v32, v34
	v_cvt_pk_bf16_f32 v61, v36, v38
	global_store_dwordx4 v[62:63], v[58:61], off offset:3072
	s_waitcnt vmcnt(8)
	s_nop 0
	v_lshl_add_u64 v[60:61], s[10:11], 0, v[210:211]
	v_add_co_u32_e32 v58, vcc, s59, v60
	v_lshl_add_u64 v[62:63], s[8:9], 0, v[210:211]
	s_nop 0
	v_addc_co_u32_e32 v59, vcc, 0, v61, vcc
	v_add_co_u32_e32 v60, vcc, s60, v60
	s_add_u32 s8, s8, 0x2000
	s_nop 0
	v_addc_co_u32_e32 v61, vcc, 0, v61, vcc
	v_add_co_u32_e32 v80, vcc, s61, v62
	s_addc_u32 s9, s9, 0
	s_nop 0
	v_addc_co_u32_e32 v81, vcc, 0, v63, vcc
	v_add_co_u32_e32 v62, vcc, s62, v62
	s_add_u32 s10, s10, 0x1000
	s_nop 0
	v_addc_co_u32_e32 v63, vcc, 0, v63, vcc
	s_addc_u32 s11, s11, 0
	s_add_i32 s43, s43, -4
	s_cmp_lg_u32 s43, 0
	v_and_b32_e32 v51, 0xffff0000, v101
	v_and_b32_e32 v29, 0xffff0000, v102
	v_and_b32_e32 v57, 0xffff0000, v103
	v_lshlrev_b32_e32 v45, 16, v100
	v_and_b32_e32 v47, 0xffff0000, v100
	v_lshlrev_b32_e32 v49, 16, v101
	v_lshlrev_b32_e32 v53, 16, v102
	v_lshlrev_b32_e32 v55, 16, v103
	v_pk_mul_f32 v[88:89], v[20:21], v[50:51]
	v_pk_mul_f32 v[92:93], v[22:23], v[28:29]
	v_pk_mul_f32 v[96:97], v[24:25], v[56:57]
	v_pk_mul_f32 v[82:83], v[14:15], v[44:45]
	v_pk_mul_f32 v[84:85], v[18:19], v[46:47]
	v_pk_mul_f32 v[86:87], v[16:17], v[48:49]
	v_pk_mul_f32 v[90:91], v[10:11], v[52:53]
	v_pk_mul_f32 v[94:95], v[12:13], v[54:55]
	v_fma_f32 v31, v9, v31, v88
	v_fma_f32 v41, v3, v41, v92
	v_fma_f32 v33, v5, v33, v96
	v_and_b32_e32 v32, 0xffff0000, v105
	v_and_b32_e32 v36, 0xffff0000, v106
	v_and_b32_e32 v40, 0xffff0000, v107
	v_fma_f32 v35, v6, v35, v82
	v_fma_f32 v37, v7, v37, v84
	v_fma_f32 v39, v8, v39, v86
	v_fma_f32 v27, v2, v27, v90
	v_fma_f32 v42, v4, v43, v94
	v_add_f32_e32 v31, v31, v89
	v_add_f32_e32 v41, v41, v93
	v_add_f32_e32 v33, v33, v97
	v_lshlrev_b32_e32 v1, 16, v104
	v_and_b32_e32 v26, 0xffff0000, v104
	v_lshlrev_b32_e32 v30, 16, v105
	v_lshlrev_b32_e32 v34, 16, v106
	v_lshlrev_b32_e32 v38, 16, v107
	v_add_f32_e32 v35, v35, v83
	v_add_f32_e32 v37, v37, v85
	v_add_f32_e32 v39, v39, v87
	v_add_f32_e32 v27, v27, v91
	v_add_f32_e32 v42, v42, v95
	v_mul_f32_e32 v31, v31, v32
	v_mul_f32_e32 v32, v41, v36
	v_mul_f32_e32 v33, v33, v40
	v_mul_f32_e32 v1, v35, v1
	v_mul_f32_e32 v26, v37, v26
	v_mul_f32_e32 v35, v39, v30
	v_mul_f32_e32 v27, v27, v34
	v_mul_f32_e32 v34, v42, v38
	v_cvt_pk_bf16_f32 v30, v1, v26
	v_cvt_pk_bf16_f32 v31, v35, v31
	v_cvt_pk_bf16_f32 v32, v27, v32
	v_cvt_pk_bf16_f32 v33, v34, v33
	global_store_dwordx4 v[80:81], v[30:33], off offset:1024
	s_nop 0
	v_mov_b32_e32 v78, v45
	v_mov_b32_e32 v76, v47
	v_mov_b32_e32 v74, v49
	v_mov_b32_e32 v72, v51
	v_mov_b32_e32 v70, v53
	v_mov_b32_e32 v68, v29
	v_mov_b32_e32 v66, v55
	v_mov_b32_e32 v64, v57
	v_lshlrev_b32_e32 v79, 16, v108
	v_and_b32_e32 v77, 0xffff0000, v108
	v_lshlrev_b32_e32 v75, 16, v109
	v_and_b32_e32 v73, 0xffff0000, v109
; __device__ __forceinline__ unsigned pk2(float lo, float hi) { return pg8::cvt_pk_bf16(lo, hi); }
;     __device__ __forceinline__ void operator()(int item) const {
;     ...
;         for (int r = 0; r < 16; ++r) { const int m = m0 + r;
;             const v4u cv = *(const v4u*)(CUB + (size_t)m * CW + ch), gv = *(const v4u*)(GZB + (size_t)m * CW + ch);
;             float cur[8], o[8];
; #pragma unroll
;             for (int e = 0; e < 4; ++e) { cur[2 * e] = pg8::bflo(cv[e]); cur[2 * e + 1] = pg8::bfhi(cv[e]); }
; #pragma unroll
;             for (int e = 0; e < 4; ++e) { o[2 * e] = pg8::bflo(gv[e]) * (w0[2 * e] * p2[2 * e] + w1[2 * e] * p1[2 * e] + w2[2 * e] * cur[2 * e]);
;                 o[2 * e + 1] = pg8::bfhi(gv[e]) * (w0[2 * e + 1] * p2[2 * e + 1] + w1[2 * e + 1] * p1[2 * e + 1] + w2[2 * e + 1] * cur[2 * e + 1]); }
;             v4u ov; ov.x = pk2(o[0], o[1]); ov.y = pk2(o[2], o[3]); ov.z = pk2(o[4], o[5]); ov.w = pk2(o[6], o[7]);
;             *(v4u*)(OAB + (size_t)m * 1024 + 512 + ch) = ov;
; #pragma unroll
;             for (int e = 0; e < 8; ++e) { p2[e] = p1[e]; p1[e] = cur[e]; }
	v_lshlrev_b32_e32 v71, 16, v110
	v_and_b32_e32 v69, 0xffff0000, v110
	v_lshlrev_b32_e32 v67, 16, v111
	v_and_b32_e32 v65, 0xffff0000, v111
	v_pk_mul_f32 v[82:83], v[14:15], v[78:79]
	v_pk_mul_f32 v[84:85], v[18:19], v[76:77]
	v_pk_mul_f32 v[86:87], v[16:17], v[74:75]
	v_pk_mul_f32 v[88:89], v[20:21], v[72:73]
	v_pk_mul_f32 v[90:91], v[10:11], v[70:71]
	v_pk_mul_f32 v[92:93], v[22:23], v[68:69]
	v_pk_mul_f32 v[94:95], v[12:13], v[66:67]
	v_pk_mul_f32 v[96:97], v[24:25], v[64:65]
	v_fma_f32 v43, v6, v44, v82
	v_fma_f32 v44, v7, v46, v84
	v_fma_f32 v46, v8, v48, v86
	v_fma_f32 v48, v9, v50, v88
	v_fma_f32 v50, v2, v52, v90
	v_fma_f32 v28, v3, v28, v92
	v_fma_f32 v52, v4, v54, v94
	v_fma_f32 v54, v5, v56, v96
	v_lshlrev_b32_e32 v1, 16, v112
	v_and_b32_e32 v27, 0xffff0000, v112
	v_lshlrev_b32_e32 v31, 16, v113
	v_and_b32_e32 v33, 0xffff0000, v113
	v_lshlrev_b32_e32 v35, 16, v114
	v_and_b32_e32 v39, 0xffff0000, v114
	v_lshlrev_b32_e32 v41, 16, v115
	v_and_b32_e32 v37, 0xffff0000, v115
	v_add_f32_e32 v43, v43, v83
	v_add_f32_e32 v44, v44, v85
	v_add_f32_e32 v46, v46, v87
	v_add_f32_e32 v48, v48, v89
	v_add_f32_e32 v50, v50, v91
	v_add_f32_e32 v28, v28, v93
	v_add_f32_e32 v52, v52, v95
	v_add_f32_e32 v54, v54, v97
	v_mul_f32_e32 v1, v43, v1
	v_mul_f32_e32 v27, v44, v27
	v_mul_f32_e32 v31, v46, v31
	v_mul_f32_e32 v33, v48, v33
	v_mul_f32_e32 v35, v50, v35
	v_mul_f32_e32 v28, v28, v39
	v_mul_f32_e32 v39, v52, v41
	v_mul_f32_e32 v37, v54, v37
	v_cvt_pk_bf16_f32 v82, v1, v27
	v_cvt_pk_bf16_f32 v83, v31, v33
	v_cvt_pk_bf16_f32 v84, v35, v28
	v_cvt_pk_bf16_f32 v85, v39, v37
	global_store_dwordx4 v[80:81], v[82:85], off offset:3072
	s_nop 0
	v_mov_b32_e32 v34, v79
	v_mov_b32_e32 v36, v77
	v_mov_b32_e32 v38, v75
	v_mov_b32_e32 v30, v73
	v_mov_b32_e32 v26, v71
	v_mov_b32_e32 v40, v69
	v_mov_b32_e32 v42, v67
	v_mov_b32_e32 v32, v65
	v_lshlrev_b32_e32 v35, 16, v116
	v_and_b32_e32 v37, 0xffff0000, v116
	v_lshlrev_b32_e32 v39, 16, v117
	v_and_b32_e32 v31, 0xffff0000, v117
	v_lshlrev_b32_e32 v27, 16, v118
	v_and_b32_e32 v41, 0xffff0000, v118
	v_lshlrev_b32_e32 v43, 16, v119
	v_and_b32_e32 v33, 0xffff0000, v119
	v_lshlrev_b32_e32 v1, 16, v120
	v_and_b32_e32 v28, 0xffff0000, v120
	v_lshlrev_b32_e32 v44, 16, v121
	v_and_b32_e32 v46, 0xffff0000, v121
	v_lshlrev_b32_e32 v48, 16, v122
	v_and_b32_e32 v50, 0xffff0000, v122
	v_lshlrev_b32_e32 v52, 16, v123
	v_and_b32_e32 v54, 0xffff0000, v123
	v_pk_mul_f32 v[80:81], v[14:15], v[34:35]
	v_pk_mul_f32 v[82:83], v[18:19], v[36:37]
	v_pk_mul_f32 v[84:85], v[16:17], v[38:39]
	v_pk_mul_f32 v[86:87], v[20:21], v[30:31]
	v_pk_mul_f32 v[88:89], v[10:11], v[26:27]
	v_pk_mul_f32 v[90:91], v[22:23], v[40:41]
	v_pk_mul_f32 v[92:93], v[12:13], v[42:43]
	v_pk_mul_f32 v[94:95], v[24:25], v[32:33]
	v_fma_f32 v26, v6, v45, v80
	v_fma_f32 v30, v7, v47, v82
	v_fma_f32 v32, v8, v49, v84
	v_fma_f32 v34, v9, v51, v86
	v_fma_f32 v36, v2, v53, v88
	v_fma_f32 v29, v3, v29, v90
	v_fma_f32 v38, v4, v55, v92
	v_fma_f32 v40, v5, v57, v94
	v_add_f32_e32 v26, v26, v81
	v_add_f32_e32 v30, v30, v83
	v_add_f32_e32 v32, v32, v85
	v_add_f32_e32 v34, v34, v87
	v_add_f32_e32 v36, v36, v89
	v_add_f32_e32 v29, v29, v91
	v_add_f32_e32 v38, v38, v93
	v_add_f32_e32 v40, v40, v95
	v_mul_f32_e32 v1, v26, v1
	v_mul_f32_e32 v26, v30, v28
	v_mul_f32_e32 v28, v32, v44
	v_mul_f32_e32 v30, v34, v46
	v_mul_f32_e32 v32, v36, v48
	v_mul_f32_e32 v29, v29, v50
	v_mul_f32_e32 v34, v38, v52
	v_mul_f32_e32 v36, v40, v54
	v_cvt_pk_bf16_f32 v44, v1, v26
	v_cvt_pk_bf16_f32 v45, v28, v30
	v_cvt_pk_bf16_f32 v46, v32, v29
	v_cvt_pk_bf16_f32 v47, v34, v36
	global_store_dwordx4 v[62:63], v[44:47], off offset:1024
	s_nop 0
	v_mov_b32_e32 v28, v35
	v_mov_b32_e32 v52, v37
	v_mov_b32_e32 v54, v39
	v_mov_b32_e32 v56, v31
	v_mov_b32_e32 v58, v27
	v_mov_b32_e32 v60, v41
	v_mov_b32_e32 v80, v43
	v_mov_b32_e32 v82, v33
	v_lshlrev_b32_e32 v29, 16, v124
	v_and_b32_e32 v53, 0xffff0000, v124
	v_lshlrev_b32_e32 v55, 16, v125
	v_and_b32_e32 v57, 0xffff0000, v125
	v_lshlrev_b32_e32 v59, 16, v126
	v_and_b32_e32 v61, 0xffff0000, v126
	v_lshlrev_b32_e32 v81, 16, v127
	v_and_b32_e32 v83, 0xffff0000, v127
	v_pk_mul_f32 v[84:85], v[14:15], v[28:29]
	v_pk_mul_f32 v[86:87], v[18:19], v[52:53]
	v_pk_mul_f32 v[88:89], v[16:17], v[54:55]
	v_pk_mul_f32 v[90:91], v[20:21], v[56:57]
	v_pk_mul_f32 v[92:93], v[10:11], v[58:59]
	v_pk_mul_f32 v[94:95], v[22:23], v[60:61]
	v_pk_mul_f32 v[96:97], v[12:13], v[80:81]
	v_pk_mul_f32 v[98:99], v[24:25], v[82:83]
	v_lshlrev_b32_e32 v1, 16, v128
	v_and_b32_e32 v26, 0xffff0000, v128
	v_lshlrev_b32_e32 v30, 16, v129
	v_and_b32_e32 v32, 0xffff0000, v129
	v_lshlrev_b32_e32 v38, 16, v131
	v_and_b32_e32 v40, 0xffff0000, v131
	v_mov_b32_e32 v44, v29
	v_mov_b32_e32 v46, v53
	v_mov_b32_e32 v48, v55
	v_fma_f32 v29, v6, v79, v84
	v_fma_f32 v42, v7, v77, v86
	v_fma_f32 v45, v8, v75, v88
	v_fma_f32 v47, v9, v73, v90
	v_fma_f32 v49, v2, v71, v92
	v_fma_f32 v51, v3, v69, v94
	v_fma_f32 v53, v4, v67, v96
	v_fma_f32 v55, v5, v65, v98
	v_lshlrev_b32_e32 v34, 16, v130
	v_and_b32_e32 v36, 0xffff0000, v130
	v_mov_b32_e32 v50, v57
	v_mov_b32_e32 v52, v59
	v_mov_b32_e32 v28, v61
	v_mov_b32_e32 v54, v81
	v_mov_b32_e32 v56, v83
	v_add_f32_e32 v29, v29, v85
	v_add_f32_e32 v42, v42, v87
	v_add_f32_e32 v45, v45, v89
	v_add_f32_e32 v47, v47, v91
	v_add_f32_e32 v49, v49, v93
	v_add_f32_e32 v51, v51, v95
	v_add_f32_e32 v53, v53, v97
	v_add_f32_e32 v55, v55, v99
	v_mul_f32_e32 v1, v29, v1
	v_mul_f32_e32 v26, v42, v26
	v_mul_f32_e32 v29, v45, v30
	v_mul_f32_e32 v30, v47, v32
	v_mul_f32_e32 v32, v49, v34
	v_mul_f32_e32 v34, v51, v36
	v_mul_f32_e32 v36, v53, v38
	v_mul_f32_e32 v38, v55, v40
	v_cvt_pk_bf16_f32 v58, v1, v26
	v_cvt_pk_bf16_f32 v59, v29, v30
	v_cvt_pk_bf16_f32 v60, v32, v34
	v_cvt_pk_bf16_f32 v61, v36, v38
	global_store_dwordx4 v[62:63], v[58:61], off offset:3072
	s_mov_b64 s[8:9], 0
